# P10 final-norm: nt cache policy on the once-read bf16 rows and the once-written f32 output stores
# speedup vs baseline: 1.0031x; 1.0028x over previous
; __device__ __forceinline__ float ss_get(const u64* p) { return (float)(*p) * (1.f / SSFIX); }
; __device__ __forceinline__ void unpack8(const u32x4 w, float (&f)[8]) { f[0] = bf_lo(w.x); f[1] = bf_hi(w.x); f[2] = bf_lo(w.y); f[3] = bf_hi(w.y); f[4] = bf_lo(w.z); f[5] = bf_hi(w.z); f[6] = bf_lo(w.w); f[7] = bf_hi(w.w); }
; __global__ void __launch_bounds__(512) mk_fwd(Args args) {
;     ...
;         for (int m = gw; m < T; m += NGW) { const u32x4* hr = (const u32x4*)(H2 + (size_t)m * DM) + lane; f32x4* xr = (f32x4*)(X + (size_t)m * DM); const float rs = __builtin_amdgcn_rsqf(pg8::ss_get(SS3 + m) * (1.f / DM) + EPS);
;             u32x4 w[4];
; #pragma unroll
;             for (int j = 0; j < 4; ++j) w[j] = hr[64 * j];
; #pragma unroll
;             for (int j = 0; j < 4; ++j) { float f[8]; unpack8(w[j], f); const int c8 = (lane + 64 * j) * 2; const f32x4 g0 = ((const f32x4*)g_final)[c8], g1 = ((const f32x4*)g_final)[c8 + 1];
;                 xr[c8] = (f32x4){f[0] * rs * g0.x, f[1] * rs * g0.y, f[2] * rs * g0.z, f[3] * rs * g0.w}; xr[c8 + 1] = (f32x4){f[4] * rs * g1.x, f[5] * rs * g1.y, f[6] * rs * g1.z, f[7] * rs * g1.w}; } }
.LBB0_1543:
	v_lshl_add_u64 v[16:17], s[10:11], 0, v[8:9]
	s_add_u32 s12, s10, s6
	s_addc_u32 s13, s11, s7
	v_add_co_u32_e32 v36, vcc, s8, v16
	global_load_dwordx4 v[12:15], v[2:3], off
	s_nop 0
	v_addc_co_u32_e32 v37, vcc, 0, v17, vcc
	global_load_dwordx2 v[38:39], v1, s[12:13]
	global_load_dwordx4 v[16:19], v[36:37], off nt
	global_load_dwordx4 v[20:23], v[2:3], off offset:16
	global_load_dwordx4 v[24:27], v[36:37], off offset:1024 nt
	global_load_dwordx4 v[28:31], v[36:37], off offset:2048 nt
	global_load_dwordx4 v[32:35], v[36:37], off offset:3072 nt
	v_add_co_u32_e32 v40, vcc, s9, v10
	s_add_i32 s28, s28, s30
	s_nop 0
	v_addc_co_u32_e32 v41, vcc, -1, v11, vcc
	s_add_u32 s6, s6, s0
	s_addc_u32 s7, s7, s1
	v_lshl_add_u64 v[8:9], v[8:9], 0, s[2:3]
	s_cmp_gt_i32 s28, 0x9fff
	s_waitcnt vmcnt(5)
	v_ffbh_u32_e32 v44, v39
	v_min_u32_e32 v44, 32, v44
	v_lshlrev_b64 v[38:39], v44, v[38:39]
	v_min_u32_e32 v38, 1, v38
	v_or_b32_e32 v38, v39, v38
	v_cvt_f32_u32_e32 v38, v38
	v_sub_u32_e32 v44, 32, v44
	s_waitcnt vmcnt(4)
	v_lshlrev_b32_e32 v36, 16, v16
	v_and_b32_e32 v37, 0xffff0000, v16
	v_ldexp_f32 v38, v38, v44
	v_mul_f32_e32 v38, 0x35800000, v38
	v_fmamk_f32 v38, v38, 0x3a000000, v0
	v_rsq_f32_e32 v38, v38
	v_lshlrev_b32_e32 v16, 16, v17
	v_and_b32_e32 v17, 0xffff0000, v17
	v_lshlrev_b32_e32 v42, 16, v18
	v_and_b32_e32 v43, 0xffff0000, v18
	v_lshlrev_b32_e32 v18, 16, v19
	v_and_b32_e32 v19, 0xffff0000, v19
	v_pk_mul_f32 v[36:37], v[38:39], v[36:37] op_sel_hi:[0,1]
	v_pk_mul_f32 v[16:17], v[38:39], v[16:17] op_sel_hi:[0,1]
	v_pk_mul_f32 v[42:43], v[38:39], v[42:43] op_sel_hi:[0,1]
	v_pk_mul_f32 v[18:19], v[38:39], v[18:19] op_sel_hi:[0,1]
	v_pk_mul_f32 v[12:13], v[36:37], v[12:13]
	v_pk_mul_f32 v[14:15], v[16:17], v[14:15]
	s_waitcnt vmcnt(3)
	v_pk_mul_f32 v[16:17], v[42:43], v[20:21]
	v_pk_mul_f32 v[18:19], v[18:19], v[22:23]
	global_store_dwordx4 v[40:41], v[12:15], off offset:-2064 nt
	global_store_dwordx4 v[40:41], v[16:19], off offset:-2048 nt
	global_load_dwordx4 v[12:15], v[2:3], off offset:2048
	s_nop 0
	global_load_dwordx4 v[16:19], v[2:3], off offset:2064
	s_waitcnt vmcnt(6)
	v_lshlrev_b32_e32 v20, 16, v24
	v_and_b32_e32 v21, 0xffff0000, v24
	v_lshlrev_b32_e32 v22, 16, v25
	v_and_b32_e32 v23, 0xffff0000, v25
	v_lshlrev_b32_e32 v24, 16, v26
	v_and_b32_e32 v25, 0xffff0000, v26
	v_lshlrev_b32_e32 v26, 16, v27
	v_and_b32_e32 v27, 0xffff0000, v27
	v_pk_mul_f32 v[20:21], v[38:39], v[20:21] op_sel_hi:[0,1]
	v_pk_mul_f32 v[22:23], v[38:39], v[22:23] op_sel_hi:[0,1]
	v_pk_mul_f32 v[24:25], v[38:39], v[24:25] op_sel_hi:[0,1]
	v_pk_mul_f32 v[26:27], v[38:39], v[26:27] op_sel_hi:[0,1]
	s_waitcnt vmcnt(1)
	v_pk_mul_f32 v[12:13], v[20:21], v[12:13]
	v_pk_mul_f32 v[14:15], v[22:23], v[14:15]
	s_waitcnt vmcnt(0)
	v_pk_mul_f32 v[16:17], v[24:25], v[16:17]
	v_pk_mul_f32 v[18:19], v[26:27], v[18:19]
	global_store_dwordx4 v[40:41], v[12:15], off offset:-16 nt
	global_store_dwordx4 v[10:11], v[16:19], off offset:-4096 nt
	global_load_dwordx4 v[12:15], v[4:5], off
	s_nop 0
	global_load_dwordx4 v[16:19], v[4:5], off offset:16
	v_lshlrev_b32_e32 v20, 16, v28
	v_and_b32_e32 v21, 0xffff0000, v28
	v_lshlrev_b32_e32 v22, 16, v29
	v_and_b32_e32 v23, 0xffff0000, v29
	v_lshlrev_b32_e32 v24, 16, v30
	v_and_b32_e32 v25, 0xffff0000, v30
	v_lshlrev_b32_e32 v26, 16, v31
	v_and_b32_e32 v27, 0xffff0000, v31
	v_pk_mul_f32 v[20:21], v[38:39], v[20:21] op_sel_hi:[0,1]
	v_pk_mul_f32 v[22:23], v[38:39], v[22:23] op_sel_hi:[0,1]
	v_pk_mul_f32 v[24:25], v[38:39], v[24:25] op_sel_hi:[0,1]
	v_pk_mul_f32 v[26:27], v[38:39], v[26:27] op_sel_hi:[0,1]
	s_waitcnt vmcnt(1)
	v_pk_mul_f32 v[12:13], v[20:21], v[12:13]
	v_pk_mul_f32 v[14:15], v[22:23], v[14:15]
	s_waitcnt vmcnt(0)
	v_pk_mul_f32 v[16:17], v[24:25], v[16:17]
	v_pk_mul_f32 v[18:19], v[26:27], v[18:19]
	global_store_dwordx4 v[10:11], v[12:15], off offset:-2064 nt
	global_store_dwordx4 v[10:11], v[16:19], off offset:-2048 nt
	global_load_dwordx4 v[12:15], v[6:7], off
	s_nop 0
	global_load_dwordx4 v[16:19], v[6:7], off offset:16
	v_lshlrev_b32_e32 v20, 16, v32
	v_and_b32_e32 v21, 0xffff0000, v32
	v_lshlrev_b32_e32 v22, 16, v33
	v_and_b32_e32 v23, 0xffff0000, v33
	v_lshlrev_b32_e32 v24, 16, v34
	v_and_b32_e32 v25, 0xffff0000, v34
	v_lshlrev_b32_e32 v26, 16, v35
	v_and_b32_e32 v27, 0xffff0000, v35
	v_pk_mul_f32 v[20:21], v[38:39], v[20:21] op_sel_hi:[0,1]
	v_pk_mul_f32 v[22:23], v[38:39], v[22:23] op_sel_hi:[0,1]
	v_pk_mul_f32 v[24:25], v[38:39], v[24:25] op_sel_hi:[0,1]
	v_pk_mul_f32 v[26:27], v[38:39], v[26:27] op_sel_hi:[0,1]
	s_waitcnt vmcnt(1)
	v_pk_mul_f32 v[12:13], v[20:21], v[12:13]
	v_pk_mul_f32 v[14:15], v[22:23], v[14:15]
	s_waitcnt vmcnt(0)
	v_pk_mul_f32 v[16:17], v[24:25], v[16:17]
	v_pk_mul_f32 v[18:19], v[26:27], v[18:19]
	global_store_dwordx4 v[10:11], v[12:15], off offset:-16 nt
	global_store_dwordx4 v[10:11], v[16:19], off nt
	v_lshl_add_u64 v[10:11], v[10:11], 0, s[4:5]
	s_cbranch_scc0 .LBB0_1543
